# v61 + strategy 9 loop-edge edit: K-loop back edge rotated (counters, exit test and next-iteration address SALU moved before the loop-back barrier) in the three GEMM K-loops
# baseline (speedup 1.0000x reference)
; #define GAS __attribute__((address_space(1)))
;     ...
;         for (int t = 0; t < nt; t += 2) {
;             const bool last = (t == nt - 2);
;             const GAS char* a1 = cA + (size_t)(t + 1) * kstep;
;             const GAS char* a2 = last ? nA : cA + (size_t)(t + 2) * kstep; const GAS char* b2 = last ? nB : cB + (size_t)(t + 2) * kstep;
;             const GAS char* a3 = a2 + kstep; const GAS char* b3 = b2 + kstep;
.LBB0_190:
	s_add_u32 s36, s34, 0xfffc0080
	s_addc_u32 s37, s35, -1
	s_add_i32 s75, 0, 0x10000
	s_cmp_eq_u32 s65, 12
	s_cselect_b32 s53, s17, s37
	s_cselect_b32 s52, s20, s36
	s_cselect_b32 s37, s25, s64
	s_cselect_b32 s36, s62, s63
	s_add_i32 s89, 0, 0x14000
	s_branch .Lrot_body_p

; #define PG8_STAGE(bufoff, gbase, voff) do { _Pragma("unroll") for (int _i = 0; _i < 2; ++_i) \
;         __builtin_amdgcn_global_load_lds((const GAS unsigned*)((const GAS char*)(gbase) + (voff)[_i]), (LAS unsigned*)(lds + (bufoff) + ldsw + _i * 8192), 16, 0, 0); } while (0)
; #define PG8_LDA(dst, b, h) do { _Pragma("unroll") for (int m = 0; m < 4; ++m) _Pragma("unroll") for (int k = 0; k < 2; ++k) dst[m][k] = *(const LAS bf16x8*)(lds + PG8_SA(b, h) + aoff + m * 2048 + k * 1024); } while (0)
; #define PG8_LDB(dst, b, h) do { _Pragma("unroll") for (int n = 0; n < 2; ++n) _Pragma("unroll") for (int k = 0; k < 2; ++k) dst[n][k] = *(const LAS bf16x8*)(lds + PG8_SB(b, h) + boff + n * 2048 + k * 1024); } while (0)
; #define PG8_MMA(ai, bj, At, Bt) do { __builtin_amdgcn_s_setprio(1); _Pragma("unroll") for (int m = 0; m < 4; ++m) _Pragma("unroll") for (int n = 0; n < 2; ++n) _Pragma("unroll") for (int k = 0; k < 2; ++k) \
;         acc[ai][bj][m][n] = __builtin_amdgcn_mfma_f32_16x16x32_bf16(Bt[n][k], At[m][k], acc[ai][bj][m][n], 0, 0, 0); __builtin_amdgcn_s_setprio(0); } while (0)
; #define PG8_WAIT_V(n) asm volatile("s_waitcnt vmcnt(" #n ")" ::: "memory")
; #define PG8_WAIT_L(n) asm volatile("s_waitcnt lgkmcnt(" #n ")" ::: "memory")
; #define PG8_BAR __builtin_amdgcn_s_barrier()
; #define PG8_SCHED __builtin_amdgcn_sched_barrier(0)
;     ...
;             PG8_LDB(B0, 0, 0); PG8_LDB(B1, 0, 1); PG8_SCHED; PG8_LDA(At, 0, 0); PG8_STAGE(PG8_SA(1, 1), a1 + hstep, voffA);
;             PG8_WAIT_V(8); PG8_WAIT_L(0); PG8_BAR; PG8_MMA(0, 0, At, B0); PG8_MMA(0, 1, At, B1); PG8_BAR; PG8_SCHED;
;             PG8_LDA(At, 0, 1); PG8_STAGE(PG8_SB(0, 0), b2, voffB); PG8_STAGE(PG8_SB(0, 1), b2 + hstep, voffB); PG8_STAGE(PG8_SA(0, 0), a2, voffA);
;             PG8_WAIT_V(8); PG8_WAIT_L(0); PG8_BAR; PG8_MMA(1, 0, At, B0); PG8_MMA(1, 1, At, B1); PG8_BAR; PG8_SCHED;
.Lrot_body_p:
	v_add_u32_e32 v156, s75, v218
	v_add_u32_e32 v172, s89, v218
	ds_read_b128 v[128:131], v156
	ds_read_b128 v[132:135], v156 offset:1024
	ds_read_b128 v[152:155], v156 offset:2048
	ds_read_b128 v[156:159], v156 offset:3072
	ds_read_b128 v[160:163], v172
	ds_read_b128 v[164:167], v172 offset:1024
	ds_read_b128 v[168:171], v172 offset:2048
	ds_read_b128 v[182:185], v172 offset:3072
	v_lshl_add_u64 v[230:231], s[34:35], 0, v[150:151]
	s_add_i32 m0, s56, 0xc000
	ds_read_b128 v[186:189], v220
	ds_read_b128 v[190:193], v220 offset:1024
	ds_read_b128 v[194:197], v220 offset:2048
	ds_read_b128 v[198:201], v220 offset:3072
	ds_read_b128 v[202:205], v220 offset:4096
	ds_read_b128 v[206:209], v220 offset:5120
	ds_read_b128 v[222:225], v220 offset:6144
	ds_read_b128 v[226:229], v220 offset:7168
	global_load_lds_dwordx4 v[230:231], off
	v_lshl_add_u64 v[230:231], s[34:35], 0, v[148:149]
	s_add_i32 m0, s56, 0xe000
	s_nop 0
	global_load_lds_dwordx4 v[230:231], off
	s_waitcnt vmcnt(8)
	s_waitcnt lgkmcnt(0)
	s_barrier
	s_setprio 1
	s_waitcnt lgkmcnt(0)
	v_mfma_f32_16x16x32_bf16 v[124:127], v[128:131], v[186:189], v[124:127]
	v_mfma_f32_16x16x32_bf16 v[120:123], v[152:155], v[186:189], v[120:123]
	v_mfma_f32_16x16x32_bf16 v[108:111], v[128:131], v[194:197], v[108:111]
	v_mfma_f32_16x16x32_bf16 v[104:107], v[152:155], v[194:197], v[104:107]
	v_mfma_f32_16x16x32_bf16 v[92:95], v[128:131], v[202:205], v[92:95]
	v_mfma_f32_16x16x32_bf16 v[88:91], v[152:155], v[202:205], v[88:91]
	v_mfma_f32_16x16x32_bf16 v[76:79], v[128:131], v[222:225], v[76:79]
	v_mfma_f32_16x16x32_bf16 v[72:75], v[152:155], v[222:225], v[72:75]
	v_mfma_f32_16x16x32_bf16 v[124:127], v[132:135], v[190:193], v[124:127]
	v_mfma_f32_16x16x32_bf16 v[120:123], v[156:159], v[190:193], v[120:123]
	v_mfma_f32_16x16x32_bf16 v[108:111], v[132:135], v[198:201], v[108:111]
	v_mfma_f32_16x16x32_bf16 v[104:107], v[156:159], v[198:201], v[104:107]
	v_mfma_f32_16x16x32_bf16 v[92:95], v[132:135], v[206:209], v[92:95]
	v_mfma_f32_16x16x32_bf16 v[88:91], v[156:159], v[206:209], v[88:91]
	v_mfma_f32_16x16x32_bf16 v[76:79], v[132:135], v[226:229], v[76:79]
	v_mfma_f32_16x16x32_bf16 v[72:75], v[156:159], v[226:229], v[72:75]
	s_setprio 0
	s_setprio 1
	v_mfma_f32_16x16x32_bf16 v[116:119], v[160:163], v[186:189], v[116:119]
	v_mfma_f32_16x16x32_bf16 v[112:115], v[168:171], v[186:189], v[112:115]
	v_mfma_f32_16x16x32_bf16 v[100:103], v[160:163], v[194:197], v[100:103]
	v_mfma_f32_16x16x32_bf16 v[96:99], v[168:171], v[194:197], v[96:99]
	v_mfma_f32_16x16x32_bf16 v[84:87], v[160:163], v[202:205], v[84:87]
	v_mfma_f32_16x16x32_bf16 v[80:83], v[168:171], v[202:205], v[80:83]
	v_mfma_f32_16x16x32_bf16 v[68:71], v[160:163], v[222:225], v[68:71]
	v_mfma_f32_16x16x32_bf16 v[64:67], v[168:171], v[222:225], v[64:67]
	v_mfma_f32_16x16x32_bf16 v[116:119], v[164:167], v[190:193], v[116:119]
	v_mfma_f32_16x16x32_bf16 v[112:115], v[182:185], v[190:193], v[112:115]
	v_mfma_f32_16x16x32_bf16 v[100:103], v[164:167], v[198:201], v[100:103]
	v_mfma_f32_16x16x32_bf16 v[96:99], v[182:185], v[198:201], v[96:99]
	v_mfma_f32_16x16x32_bf16 v[84:87], v[164:167], v[206:209], v[84:87]
	v_mfma_f32_16x16x32_bf16 v[80:83], v[182:185], v[206:209], v[80:83]
	v_mfma_f32_16x16x32_bf16 v[68:71], v[164:167], v[226:229], v[68:71]
	v_mfma_f32_16x16x32_bf16 v[64:67], v[182:185], v[226:229], v[64:67]
	s_setprio 0
	s_barrier
	s_add_i32 s75, s75, s95
	v_lshl_add_u64 v[230:231], s[36:37], 0, v[138:139]
	s_mov_b32 m0, s75
	ds_read_b128 v[186:189], v220 offset:16384
	ds_read_b128 v[190:193], v220 offset:17408
	ds_read_b128 v[194:197], v220 offset:18432
	ds_read_b128 v[198:201], v220 offset:19456
	ds_read_b128 v[202:205], v220 offset:20480
	ds_read_b128 v[206:209], v220 offset:21504
	ds_read_b128 v[222:225], v220 offset:22528
	ds_read_b128 v[226:229], v220 offset:23552
	global_load_lds_dwordx4 v[230:231], off
	s_add_i32 m0, s75, 0x2000
	s_add_u32 s90, s36, 0x40000
	v_lshl_add_u64 v[232:233], s[36:37], 0, v[142:143]
	s_addc_u32 s91, s37, 0
	s_add_i32 s75, s89, s95
	global_load_lds_dwordx4 v[232:233], off
	v_lshl_add_u64 v[234:235], s[90:91], 0, v[138:139]
	s_mov_b32 m0, s75
	v_lshl_add_u64 v[236:237], s[52:53], 0, v[140:141]
	global_load_lds_dwordx4 v[234:235], off
	v_lshl_add_u64 v[234:235], s[90:91], 0, v[142:143]
	s_add_i32 m0, s75, 0x2000
	s_nop 0
	global_load_lds_dwordx4 v[234:235], off
	v_lshl_add_u64 v[234:235], s[52:53], 0, v[136:137]
	s_mov_b32 m0, s56
	s_nop 0
	global_load_lds_dwordx4 v[234:235], off
	s_mov_b32 m0, s57
	s_nop 0
	global_load_lds_dwordx4 v[236:237], off
	s_waitcnt vmcnt(8)
	s_waitcnt lgkmcnt(0)
	s_barrier
; #define PG8_STAGE(bufoff, gbase, voff) do { _Pragma("unroll") for (int _i = 0; _i < 2; ++_i) \
;         __builtin_amdgcn_global_load_lds((const GAS unsigned*)((const GAS char*)(gbase) + (voff)[_i]), (LAS unsigned*)(lds + (bufoff) + ldsw + _i * 8192), 16, 0, 0); } while (0)
; #define PG8_LDA(dst, b, h) do { _Pragma("unroll") for (int m = 0; m < 4; ++m) _Pragma("unroll") for (int k = 0; k < 2; ++k) dst[m][k] = *(const LAS bf16x8*)(lds + PG8_SA(b, h) + aoff + m * 2048 + k * 1024); } while (0)
; #define PG8_LDB(dst, b, h) do { _Pragma("unroll") for (int n = 0; n < 2; ++n) _Pragma("unroll") for (int k = 0; k < 2; ++k) dst[n][k] = *(const LAS bf16x8*)(lds + PG8_SB(b, h) + boff + n * 2048 + k * 1024); } while (0)
; #define PG8_MMA(ai, bj, At, Bt) do { __builtin_amdgcn_s_setprio(1); _Pragma("unroll") for (int m = 0; m < 4; ++m) _Pragma("unroll") for (int n = 0; n < 2; ++n) _Pragma("unroll") for (int k = 0; k < 2; ++k) \
;         acc[ai][bj][m][n] = __builtin_amdgcn_mfma_f32_16x16x32_bf16(Bt[n][k], At[m][k], acc[ai][bj][m][n], 0, 0, 0); __builtin_amdgcn_s_setprio(0); } while (0)
; #define PG8_WAIT_V(n) asm volatile("s_waitcnt vmcnt(" #n ")" ::: "memory")
; #define PG8_WAIT_L(n) asm volatile("s_waitcnt lgkmcnt(" #n ")" ::: "memory")
; #define PG8_BAR __builtin_amdgcn_s_barrier()
; #define PG8_SCHED __builtin_amdgcn_sched_barrier(0)
;     ...
;             PG8_WAIT_V(8); PG8_WAIT_L(0); PG8_BAR; PG8_MMA(1, 0, At, B0); PG8_MMA(1, 1, At, B1); PG8_BAR; PG8_SCHED;
;             PG8_LDB(B0, 1, 0); PG8_LDB(B1, 1, 1); PG8_SCHED; PG8_LDA(At, 1, 0); PG8_STAGE(PG8_SA(0, 1), a2 + hstep, voffA);
;             PG8_WAIT_V(8); PG8_WAIT_L(0); PG8_BAR; PG8_MMA(0, 0, At, B0); PG8_MMA(0, 1, At, B1); PG8_BAR; PG8_SCHED;
	s_setprio 1
	s_waitcnt lgkmcnt(0)
	v_mfma_f32_16x16x32_bf16 v[60:63], v[128:131], v[186:189], v[60:63]
	v_mfma_f32_16x16x32_bf16 v[56:59], v[152:155], v[186:189], v[56:59]
	v_mfma_f32_16x16x32_bf16 v[44:47], v[128:131], v[194:197], v[44:47]
	v_mfma_f32_16x16x32_bf16 v[40:43], v[152:155], v[194:197], v[40:43]
	v_mfma_f32_16x16x32_bf16 v[28:31], v[128:131], v[202:205], v[28:31]
	v_mfma_f32_16x16x32_bf16 v[24:27], v[152:155], v[202:205], v[24:27]
	v_mfma_f32_16x16x32_bf16 v[12:15], v[128:131], v[222:225], v[12:15]
	v_mfma_f32_16x16x32_bf16 v[8:11], v[152:155], v[222:225], v[8:11]
	v_mfma_f32_16x16x32_bf16 v[60:63], v[132:135], v[190:193], v[60:63]
	v_mfma_f32_16x16x32_bf16 v[56:59], v[156:159], v[190:193], v[56:59]
	v_mfma_f32_16x16x32_bf16 v[44:47], v[132:135], v[198:201], v[44:47]
	v_mfma_f32_16x16x32_bf16 v[40:43], v[156:159], v[198:201], v[40:43]
	v_mfma_f32_16x16x32_bf16 v[28:31], v[132:135], v[206:209], v[28:31]
	v_mfma_f32_16x16x32_bf16 v[24:27], v[156:159], v[206:209], v[24:27]
	v_mfma_f32_16x16x32_bf16 v[12:15], v[132:135], v[226:229], v[12:15]
	v_mfma_f32_16x16x32_bf16 v[8:11], v[156:159], v[226:229], v[8:11]
	s_setprio 0
	s_setprio 1
	v_mfma_f32_16x16x32_bf16 v[52:55], v[160:163], v[186:189], v[52:55]
	v_mfma_f32_16x16x32_bf16 v[48:51], v[168:171], v[186:189], v[48:51]
	v_mfma_f32_16x16x32_bf16 v[36:39], v[160:163], v[194:197], v[36:39]
	v_mfma_f32_16x16x32_bf16 v[32:35], v[168:171], v[194:197], v[32:35]
	v_mfma_f32_16x16x32_bf16 v[20:23], v[160:163], v[202:205], v[20:23]
	v_mfma_f32_16x16x32_bf16 v[16:19], v[168:171], v[202:205], v[16:19]
	v_mfma_f32_16x16x32_bf16 v[4:7], v[160:163], v[222:225], v[4:7]
	v_mfma_f32_16x16x32_bf16 v[0:3], v[168:171], v[222:225], v[0:3]
	v_mfma_f32_16x16x32_bf16 v[52:55], v[164:167], v[190:193], v[52:55]
	v_mfma_f32_16x16x32_bf16 v[48:51], v[182:185], v[190:193], v[48:51]
	v_mfma_f32_16x16x32_bf16 v[36:39], v[164:167], v[198:201], v[36:39]
	v_mfma_f32_16x16x32_bf16 v[32:35], v[182:185], v[198:201], v[32:35]
	v_mfma_f32_16x16x32_bf16 v[20:23], v[164:167], v[206:209], v[20:23]
	v_mfma_f32_16x16x32_bf16 v[16:19], v[182:185], v[206:209], v[16:19]
	v_mfma_f32_16x16x32_bf16 v[4:7], v[164:167], v[226:229], v[4:7]
	v_mfma_f32_16x16x32_bf16 v[0:3], v[182:185], v[226:229], v[0:3]
	s_setprio 0
	s_barrier
	s_add_i32 s75, 0, 0x18000
	s_add_i32 s89, 0, 0x1c000
	v_add_u32_e32 v156, s75, v218
	v_add_u32_e32 v172, s89, v218
	ds_read_b128 v[128:131], v156
	ds_read_b128 v[132:135], v156 offset:1024
	ds_read_b128 v[152:155], v156 offset:2048
	ds_read_b128 v[156:159], v156 offset:3072
	ds_read_b128 v[160:163], v172
	ds_read_b128 v[164:167], v172 offset:1024
	ds_read_b128 v[168:171], v172 offset:2048
	ds_read_b128 v[182:185], v172 offset:3072
	s_add_u32 s52, s52, 0x40000
	s_addc_u32 s53, s53, 0
	s_mov_b32 m0, s69
	v_lshl_add_u64 v[238:239], s[52:53], 0, v[136:137]
	ds_read_b128 v[186:189], v220 offset:32768
	ds_read_b128 v[190:193], v220 offset:33792
	ds_read_b128 v[194:197], v220 offset:34816
	ds_read_b128 v[198:201], v220 offset:35840
	ds_read_b128 v[202:205], v220 offset:36864
	ds_read_b128 v[206:209], v220 offset:37888
	ds_read_b128 v[222:225], v220 offset:38912
	ds_read_b128 v[226:229], v220 offset:39936
	global_load_lds_dwordx4 v[238:239], off
	v_lshl_add_u64 v[238:239], s[52:53], 0, v[140:141]
	s_mov_b32 m0, s66
	s_nop 0
	global_load_lds_dwordx4 v[238:239], off
	s_waitcnt vmcnt(8)
	s_waitcnt lgkmcnt(0)
	s_barrier
	s_setprio 1
	s_waitcnt lgkmcnt(0)
	v_mfma_f32_16x16x32_bf16 v[124:127], v[128:131], v[186:189], v[124:127]
	v_mfma_f32_16x16x32_bf16 v[120:123], v[152:155], v[186:189], v[120:123]
	v_mfma_f32_16x16x32_bf16 v[108:111], v[128:131], v[194:197], v[108:111]
	v_mfma_f32_16x16x32_bf16 v[104:107], v[152:155], v[194:197], v[104:107]
	v_mfma_f32_16x16x32_bf16 v[92:95], v[128:131], v[202:205], v[92:95]
	v_mfma_f32_16x16x32_bf16 v[88:91], v[152:155], v[202:205], v[88:91]
	v_mfma_f32_16x16x32_bf16 v[76:79], v[128:131], v[222:225], v[76:79]
	v_mfma_f32_16x16x32_bf16 v[72:75], v[152:155], v[222:225], v[72:75]
	v_mfma_f32_16x16x32_bf16 v[124:127], v[132:135], v[190:193], v[124:127]
	v_mfma_f32_16x16x32_bf16 v[120:123], v[156:159], v[190:193], v[120:123]
	v_mfma_f32_16x16x32_bf16 v[108:111], v[132:135], v[198:201], v[108:111]
	v_mfma_f32_16x16x32_bf16 v[104:107], v[156:159], v[198:201], v[104:107]
	v_mfma_f32_16x16x32_bf16 v[92:95], v[132:135], v[206:209], v[92:95]
	v_mfma_f32_16x16x32_bf16 v[88:91], v[156:159], v[206:209], v[88:91]
	v_mfma_f32_16x16x32_bf16 v[76:79], v[132:135], v[226:229], v[76:79]
	v_mfma_f32_16x16x32_bf16 v[72:75], v[156:159], v[226:229], v[72:75]
	s_setprio 0
	s_setprio 1
	v_mfma_f32_16x16x32_bf16 v[116:119], v[160:163], v[186:189], v[116:119]
	v_mfma_f32_16x16x32_bf16 v[112:115], v[168:171], v[186:189], v[112:115]
	v_mfma_f32_16x16x32_bf16 v[100:103], v[160:163], v[194:197], v[100:103]
	v_mfma_f32_16x16x32_bf16 v[96:99], v[168:171], v[194:197], v[96:99]
	v_mfma_f32_16x16x32_bf16 v[84:87], v[160:163], v[202:205], v[84:87]
	v_mfma_f32_16x16x32_bf16 v[80:83], v[168:171], v[202:205], v[80:83]
	v_mfma_f32_16x16x32_bf16 v[68:71], v[160:163], v[222:225], v[68:71]
	v_mfma_f32_16x16x32_bf16 v[64:67], v[168:171], v[222:225], v[64:67]
	v_mfma_f32_16x16x32_bf16 v[116:119], v[164:167], v[190:193], v[116:119]
	v_mfma_f32_16x16x32_bf16 v[112:115], v[182:185], v[190:193], v[112:115]
	v_mfma_f32_16x16x32_bf16 v[100:103], v[164:167], v[198:201], v[100:103]
	v_mfma_f32_16x16x32_bf16 v[96:99], v[182:185], v[198:201], v[96:99]
	v_mfma_f32_16x16x32_bf16 v[84:87], v[164:167], v[206:209], v[84:87]
	v_mfma_f32_16x16x32_bf16 v[80:83], v[182:185], v[206:209], v[80:83]
	v_mfma_f32_16x16x32_bf16 v[68:71], v[164:167], v[226:229], v[68:71]
	v_mfma_f32_16x16x32_bf16 v[64:67], v[182:185], v[226:229], v[64:67]
	s_setprio 0
	s_barrier
; #define GAS __attribute__((address_space(1)))
; #define PG8_STAGE(bufoff, gbase, voff) do { _Pragma("unroll") for (int _i = 0; _i < 2; ++_i) \
;         __builtin_amdgcn_global_load_lds((const GAS unsigned*)((const GAS char*)(gbase) + (voff)[_i]), (LAS unsigned*)(lds + (bufoff) + ldsw + _i * 8192), 16, 0, 0); } while (0)
; #define PG8_LDA(dst, b, h) do { _Pragma("unroll") for (int m = 0; m < 4; ++m) _Pragma("unroll") for (int k = 0; k < 2; ++k) dst[m][k] = *(const LAS bf16x8*)(lds + PG8_SA(b, h) + aoff + m * 2048 + k * 1024); } while (0)
; #define PG8_MMA(ai, bj, At, Bt) do { __builtin_amdgcn_s_setprio(1); _Pragma("unroll") for (int m = 0; m < 4; ++m) _Pragma("unroll") for (int n = 0; n < 2; ++n) _Pragma("unroll") for (int k = 0; k < 2; ++k) \
;         acc[ai][bj][m][n] = __builtin_amdgcn_mfma_f32_16x16x32_bf16(Bt[n][k], At[m][k], acc[ai][bj][m][n], 0, 0, 0); __builtin_amdgcn_s_setprio(0); } while (0)
; #define PG8_WAIT_V(n) asm volatile("s_waitcnt vmcnt(" #n ")" ::: "memory")
; #define PG8_WAIT_L(n) asm volatile("s_waitcnt lgkmcnt(" #n ")" ::: "memory")
; #define PG8_BAR __builtin_amdgcn_s_barrier()
; #define PG8_SCHED __builtin_amdgcn_sched_barrier(0)
;     ...
;         for (int t = 0; t < nt; t += 2) {
;             const bool last = (t == nt - 2);
;             const GAS char* a1 = cA + (size_t)(t + 1) * kstep;
;             const GAS char* a2 = last ? nA : cA + (size_t)(t + 2) * kstep; const GAS char* b2 = last ? nB : cB + (size_t)(t + 2) * kstep;
;             const GAS char* a3 = a2 + kstep; const GAS char* b3 = b2 + kstep;
;     ...
;             PG8_LDA(At, 1, 1); PG8_STAGE(PG8_SB(1, 0), b3, voffB); PG8_STAGE(PG8_SB(1, 1), b3 + hstep, voffB); PG8_STAGE(PG8_SA(1, 0), a3, voffA);
;             PG8_WAIT_V(8); PG8_WAIT_L(0); PG8_BAR; PG8_MMA(1, 0, At, B0); PG8_MMA(1, 1, At, B1); PG8_BAR; PG8_SCHED;
;         }
;         if (wr == 0) PG8_BAR;
	s_add_i32 s52, s75, s95
	v_lshl_add_u64 v[230:231], v[230:231], 0, s[82:83]
	s_mov_b32 m0, s52
	ds_read_b128 v[186:189], v220 offset:49152
	ds_read_b128 v[190:193], v220 offset:50176
	ds_read_b128 v[194:197], v220 offset:51200
	ds_read_b128 v[198:201], v220 offset:52224
	ds_read_b128 v[202:205], v220 offset:53248
	ds_read_b128 v[206:209], v220 offset:54272
	ds_read_b128 v[222:225], v220 offset:55296
	ds_read_b128 v[226:229], v220 offset:56320
	global_load_lds_dwordx4 v[230:231], off
	s_add_i32 m0, s52, 0x2000
	s_add_u32 s36, s36, 0x40080
	v_lshl_add_u64 v[230:231], v[232:233], 0, s[82:83]
	s_addc_u32 s37, s37, 0
	s_add_i32 s52, s89, s95
	global_load_lds_dwordx4 v[230:231], off
	v_lshl_add_u64 v[230:231], s[36:37], 0, v[138:139]
	s_mov_b32 m0, s52
	s_nop 0
	global_load_lds_dwordx4 v[230:231], off
	v_lshl_add_u64 v[230:231], s[36:37], 0, v[142:143]
	s_add_i32 m0, s52, 0x2000
	s_nop 0
	global_load_lds_dwordx4 v[230:231], off
	v_lshl_add_u64 v[230:231], v[234:235], 0, s[82:83]
	s_mov_b32 m0, s67
	s_nop 0
	global_load_lds_dwordx4 v[230:231], off
	v_lshl_add_u64 v[230:231], v[236:237], 0, s[82:83]
	s_mov_b32 m0, s12
	s_nop 0
	global_load_lds_dwordx4 v[230:231], off
	s_waitcnt vmcnt(8)
	s_waitcnt lgkmcnt(0)
	s_barrier
	s_setprio 1
	s_waitcnt lgkmcnt(0)
	v_mfma_f32_16x16x32_bf16 v[60:63], v[128:131], v[186:189], v[60:63]
	v_mfma_f32_16x16x32_bf16 v[56:59], v[152:155], v[186:189], v[56:59]
	v_mfma_f32_16x16x32_bf16 v[44:47], v[128:131], v[194:197], v[44:47]
	v_mfma_f32_16x16x32_bf16 v[40:43], v[152:155], v[194:197], v[40:43]
	v_mfma_f32_16x16x32_bf16 v[28:31], v[128:131], v[202:205], v[28:31]
	v_mfma_f32_16x16x32_bf16 v[24:27], v[152:155], v[202:205], v[24:27]
	v_mfma_f32_16x16x32_bf16 v[12:15], v[128:131], v[222:225], v[12:15]
	v_mfma_f32_16x16x32_bf16 v[8:11], v[152:155], v[222:225], v[8:11]
	v_mfma_f32_16x16x32_bf16 v[60:63], v[132:135], v[190:193], v[60:63]
	v_mfma_f32_16x16x32_bf16 v[56:59], v[156:159], v[190:193], v[56:59]
	v_mfma_f32_16x16x32_bf16 v[44:47], v[132:135], v[198:201], v[44:47]
	v_mfma_f32_16x16x32_bf16 v[40:43], v[156:159], v[198:201], v[40:43]
	v_mfma_f32_16x16x32_bf16 v[28:31], v[132:135], v[206:209], v[28:31]
	v_mfma_f32_16x16x32_bf16 v[24:27], v[156:159], v[206:209], v[24:27]
	v_mfma_f32_16x16x32_bf16 v[12:15], v[132:135], v[226:229], v[12:15]
	v_mfma_f32_16x16x32_bf16 v[8:11], v[156:159], v[226:229], v[8:11]
	s_setprio 0
	s_setprio 1
	v_mfma_f32_16x16x32_bf16 v[52:55], v[160:163], v[186:189], v[52:55]
	v_mfma_f32_16x16x32_bf16 v[48:51], v[168:171], v[186:189], v[48:51]
	v_mfma_f32_16x16x32_bf16 v[36:39], v[160:163], v[194:197], v[36:39]
	v_mfma_f32_16x16x32_bf16 v[32:35], v[168:171], v[194:197], v[32:35]
	v_mfma_f32_16x16x32_bf16 v[20:23], v[160:163], v[202:205], v[20:23]
	v_mfma_f32_16x16x32_bf16 v[16:19], v[168:171], v[202:205], v[16:19]
	v_mfma_f32_16x16x32_bf16 v[4:7], v[160:163], v[222:225], v[4:7]
	v_mfma_f32_16x16x32_bf16 v[0:3], v[168:171], v[222:225], v[0:3]
	v_mfma_f32_16x16x32_bf16 v[52:55], v[164:167], v[190:193], v[52:55]
	v_mfma_f32_16x16x32_bf16 v[48:51], v[182:185], v[190:193], v[48:51]
	v_mfma_f32_16x16x32_bf16 v[36:39], v[164:167], v[198:201], v[36:39]
	v_mfma_f32_16x16x32_bf16 v[32:35], v[182:185], v[198:201], v[32:35]
	v_mfma_f32_16x16x32_bf16 v[20:23], v[164:167], v[206:209], v[20:23]
	v_mfma_f32_16x16x32_bf16 v[16:19], v[182:185], v[206:209], v[16:19]
	v_mfma_f32_16x16x32_bf16 v[4:7], v[164:167], v[226:229], v[4:7]
	v_mfma_f32_16x16x32_bf16 v[0:3], v[182:185], v[226:229], v[0:3]
	s_setprio 0
	s_add_i32 s65, s65, 2
	s_add_u32 s63, s63, 0x100
	s_addc_u32 s64, s64, 0
	s_add_u32 s34, s34, 0x100
	s_addc_u32 s35, s35, 0
	s_cmp_gt_u32 s65, 13
	s_cbranch_scc1 .Lrot_exit_p
	s_add_u32 s36, s34, 0xfffc0080
	s_addc_u32 s37, s35, -1
	s_add_i32 s75, 0, 0x10000
	s_cmp_eq_u32 s65, 12
	s_cselect_b32 s53, s17, s37
	s_cselect_b32 s52, s20, s36
	s_cselect_b32 s37, s25, s64
	s_cselect_b32 s36, s62, s63
	s_add_i32 s89, 0, 0x14000
	s_branch .Lrot_head_p
.Lrot_exit_p:
	s_barrier
	v_readlane_b32 s34, v243, 62
	v_readlane_b32 s35, v243, 63
	s_and_b64 vcc, exec, s[34:35]
	s_cbranch_vccz .LBB0_193
	s_barrier

; #define GAS __attribute__((address_space(1)))
;     ...
;         for (int t = 0; t < nt; t += 2) {
;             const bool last = (t == nt - 2);
;             const GAS char* a1 = cA + (size_t)(t + 1) * kstep;
;             const GAS char* a2 = last ? nA : cA + (size_t)(t + 2) * kstep; const GAS char* b2 = last ? nB : cB + (size_t)(t + 2) * kstep;
;             const GAS char* a3 = a2 + kstep; const GAS char* b3 = b2 + kstep;
.LBB0_957:
	s_add_u32 s53, s62, 0xfffc0080
	s_addc_u32 s64, s63, -1
	s_add_i32 s90, 0, 0x10000
	s_cmp_eq_u32 s25, 12
	s_cselect_b32 s67, s27, s64
	s_cselect_b32 s66, s26, s53
	s_cselect_b32 s65, s37, s17
	s_cselect_b32 s64, s36, s13
	s_add_i32 s53, 0, 0x14000
	s_branch .Lrot_body_m

; #define PG8_STAGE(bufoff, gbase, voff) do { _Pragma("unroll") for (int _i = 0; _i < 2; ++_i) \
;         __builtin_amdgcn_global_load_lds((const GAS unsigned*)((const GAS char*)(gbase) + (voff)[_i]), (LAS unsigned*)(lds + (bufoff) + ldsw + _i * 8192), 16, 0, 0); } while (0)
; #define PG8_LDA(dst, b, h) do { _Pragma("unroll") for (int m = 0; m < 4; ++m) _Pragma("unroll") for (int k = 0; k < 2; ++k) dst[m][k] = *(const LAS bf16x8*)(lds + PG8_SA(b, h) + aoff + m * 2048 + k * 1024); } while (0)
; #define PG8_LDB(dst, b, h) do { _Pragma("unroll") for (int n = 0; n < 2; ++n) _Pragma("unroll") for (int k = 0; k < 2; ++k) dst[n][k] = *(const LAS bf16x8*)(lds + PG8_SB(b, h) + boff + n * 2048 + k * 1024); } while (0)
; #define PG8_MMA(ai, bj, At, Bt) do { __builtin_amdgcn_s_setprio(1); _Pragma("unroll") for (int m = 0; m < 4; ++m) _Pragma("unroll") for (int n = 0; n < 2; ++n) _Pragma("unroll") for (int k = 0; k < 2; ++k) \
;         acc[ai][bj][m][n] = __builtin_amdgcn_mfma_f32_16x16x32_bf16(Bt[n][k], At[m][k], acc[ai][bj][m][n], 0, 0, 0); __builtin_amdgcn_s_setprio(0); } while (0)
; #define PG8_WAIT_V(n) asm volatile("s_waitcnt vmcnt(" #n ")" ::: "memory")
; #define PG8_WAIT_L(n) asm volatile("s_waitcnt lgkmcnt(" #n ")" ::: "memory")
; #define PG8_BAR __builtin_amdgcn_s_barrier()
; #define PG8_SCHED __builtin_amdgcn_sched_barrier(0)
;     ...
;             PG8_LDB(B0, 0, 0); PG8_LDB(B1, 0, 1); PG8_SCHED; PG8_LDA(At, 0, 0); PG8_STAGE(PG8_SA(1, 1), a1 + hstep, voffA);
;             PG8_WAIT_V(8); PG8_WAIT_L(0); PG8_BAR; PG8_MMA(0, 0, At, B0); PG8_MMA(0, 1, At, B1); PG8_BAR; PG8_SCHED;
;             PG8_LDA(At, 0, 1); PG8_STAGE(PG8_SB(0, 0), b2, voffB); PG8_STAGE(PG8_SB(0, 1), b2 + hstep, voffB); PG8_STAGE(PG8_SA(0, 0), a2, voffA);
;             PG8_WAIT_V(8); PG8_WAIT_L(0); PG8_BAR; PG8_MMA(1, 0, At, B0); PG8_MMA(1, 1, At, B1); PG8_BAR; PG8_SCHED;
.Lrot_body_m:
	v_add_u32_e32 v140, s90, v195
	v_add_u32_e32 v156, s53, v195
	ds_read_b128 v[128:131], v140
	ds_read_b128 v[132:135], v140 offset:1024
	ds_read_b128 v[136:139], v140 offset:2048
	ds_read_b128 v[140:143], v140 offset:3072
	ds_read_b128 v[144:147], v156
	ds_read_b128 v[148:151], v156 offset:1024
	ds_read_b128 v[152:155], v156 offset:2048
	ds_read_b128 v[156:159], v156 offset:3072
	v_lshl_add_u64 v[170:171], s[62:63], 0, v[168:169]
	s_add_i32 m0, s69, 0xc000
	ds_read_b128 v[182:185], v197
	ds_read_b128 v[186:189], v197 offset:1024
	ds_read_b128 v[190:193], v197 offset:2048
	ds_read_b128 v[198:201], v197 offset:3072
	ds_read_b128 v[202:205], v197 offset:4096
	ds_read_b128 v[206:209], v197 offset:5120
	ds_read_b128 v[218:221], v197 offset:6144
	ds_read_b128 v[222:225], v197 offset:7168
	global_load_lds_dwordx4 v[170:171], off
	v_lshl_add_u64 v[170:171], s[62:63], 0, v[166:167]
	s_add_i32 m0, s69, 0xe000
	s_nop 0
	global_load_lds_dwordx4 v[170:171], off
	s_waitcnt vmcnt(8)
	s_waitcnt lgkmcnt(0)
	s_barrier
	s_setprio 1
	s_waitcnt lgkmcnt(0)
	v_mfma_f32_16x16x32_bf16 v[124:127], v[128:131], v[182:185], v[124:127]
	v_mfma_f32_16x16x32_bf16 v[120:123], v[136:139], v[182:185], v[120:123]
	v_mfma_f32_16x16x32_bf16 v[116:119], v[128:131], v[190:193], v[116:119]
	v_mfma_f32_16x16x32_bf16 v[112:115], v[136:139], v[190:193], v[112:115]
	v_mfma_f32_16x16x32_bf16 v[108:111], v[128:131], v[202:205], v[108:111]
	v_mfma_f32_16x16x32_bf16 v[104:107], v[136:139], v[202:205], v[104:107]
	v_mfma_f32_16x16x32_bf16 v[100:103], v[128:131], v[218:221], v[100:103]
	v_mfma_f32_16x16x32_bf16 v[96:99], v[136:139], v[218:221], v[96:99]
	v_mfma_f32_16x16x32_bf16 v[124:127], v[132:135], v[186:189], v[124:127]
	v_mfma_f32_16x16x32_bf16 v[120:123], v[140:143], v[186:189], v[120:123]
	v_mfma_f32_16x16x32_bf16 v[116:119], v[132:135], v[198:201], v[116:119]
	v_mfma_f32_16x16x32_bf16 v[112:115], v[140:143], v[198:201], v[112:115]
	v_mfma_f32_16x16x32_bf16 v[108:111], v[132:135], v[206:209], v[108:111]
	v_mfma_f32_16x16x32_bf16 v[104:107], v[140:143], v[206:209], v[104:107]
	v_mfma_f32_16x16x32_bf16 v[100:103], v[132:135], v[222:225], v[100:103]
	v_mfma_f32_16x16x32_bf16 v[96:99], v[140:143], v[222:225], v[96:99]
	s_setprio 0
	s_setprio 1
	v_mfma_f32_16x16x32_bf16 v[92:95], v[144:147], v[182:185], v[92:95]
	v_mfma_f32_16x16x32_bf16 v[88:91], v[152:155], v[182:185], v[88:91]
	v_mfma_f32_16x16x32_bf16 v[84:87], v[144:147], v[190:193], v[84:87]
	v_mfma_f32_16x16x32_bf16 v[80:83], v[152:155], v[190:193], v[80:83]
	v_mfma_f32_16x16x32_bf16 v[76:79], v[144:147], v[202:205], v[76:79]
	v_mfma_f32_16x16x32_bf16 v[72:75], v[152:155], v[202:205], v[72:75]
	v_mfma_f32_16x16x32_bf16 v[68:71], v[144:147], v[218:221], v[68:71]
	v_mfma_f32_16x16x32_bf16 v[64:67], v[152:155], v[218:221], v[64:67]
	v_mfma_f32_16x16x32_bf16 v[92:95], v[148:151], v[186:189], v[92:95]
	v_mfma_f32_16x16x32_bf16 v[88:91], v[156:159], v[186:189], v[88:91]
	v_mfma_f32_16x16x32_bf16 v[84:87], v[148:151], v[198:201], v[84:87]
	v_mfma_f32_16x16x32_bf16 v[80:83], v[156:159], v[198:201], v[80:83]
	v_mfma_f32_16x16x32_bf16 v[76:79], v[148:151], v[206:209], v[76:79]
	v_mfma_f32_16x16x32_bf16 v[72:75], v[156:159], v[206:209], v[72:75]
	v_mfma_f32_16x16x32_bf16 v[68:71], v[148:151], v[222:225], v[68:71]
	v_mfma_f32_16x16x32_bf16 v[64:67], v[156:159], v[222:225], v[64:67]
	s_setprio 0
	s_barrier
	s_add_i32 s90, s90, s95
	v_lshl_add_u64 v[170:171], s[64:65], 0, v[172:173]
	s_mov_b32 m0, s90
	ds_read_b128 v[182:185], v197 offset:16384
	ds_read_b128 v[186:189], v197 offset:17408
	ds_read_b128 v[190:193], v197 offset:18432
	ds_read_b128 v[198:201], v197 offset:19456
	ds_read_b128 v[202:205], v197 offset:20480
	ds_read_b128 v[206:209], v197 offset:21504
	ds_read_b128 v[218:221], v197 offset:22528
	ds_read_b128 v[222:225], v197 offset:23552
	global_load_lds_dwordx4 v[170:171], off
	s_add_i32 m0, s90, 0x2000
	s_add_u32 s90, s64, 0x40000
	v_lshl_add_u64 v[226:227], s[64:65], 0, v[164:165]
	s_addc_u32 s91, s65, 0
	s_add_i32 s53, s53, s95
	global_load_lds_dwordx4 v[226:227], off
	v_lshl_add_u64 v[228:229], s[90:91], 0, v[172:173]
	s_mov_b32 m0, s53
	v_lshl_add_u64 v[230:231], s[66:67], 0, v[162:163]
	global_load_lds_dwordx4 v[228:229], off
	v_lshl_add_u64 v[228:229], s[90:91], 0, v[164:165]
	s_add_i32 m0, s53, 0x2000
	s_nop 0
	global_load_lds_dwordx4 v[228:229], off
	v_lshl_add_u64 v[228:229], s[66:67], 0, v[160:161]
	s_mov_b32 m0, s69
	s_nop 0
	global_load_lds_dwordx4 v[228:229], off
	s_mov_b32 m0, s70
	s_nop 0
	global_load_lds_dwordx4 v[230:231], off
	s_waitcnt vmcnt(8)
	s_waitcnt lgkmcnt(0)
	s_barrier
; #define PG8_STAGE(bufoff, gbase, voff) do { _Pragma("unroll") for (int _i = 0; _i < 2; ++_i) \
;         __builtin_amdgcn_global_load_lds((const GAS unsigned*)((const GAS char*)(gbase) + (voff)[_i]), (LAS unsigned*)(lds + (bufoff) + ldsw + _i * 8192), 16, 0, 0); } while (0)
; #define PG8_LDA(dst, b, h) do { _Pragma("unroll") for (int m = 0; m < 4; ++m) _Pragma("unroll") for (int k = 0; k < 2; ++k) dst[m][k] = *(const LAS bf16x8*)(lds + PG8_SA(b, h) + aoff + m * 2048 + k * 1024); } while (0)
; #define PG8_LDB(dst, b, h) do { _Pragma("unroll") for (int n = 0; n < 2; ++n) _Pragma("unroll") for (int k = 0; k < 2; ++k) dst[n][k] = *(const LAS bf16x8*)(lds + PG8_SB(b, h) + boff + n * 2048 + k * 1024); } while (0)
; #define PG8_MMA(ai, bj, At, Bt) do { __builtin_amdgcn_s_setprio(1); _Pragma("unroll") for (int m = 0; m < 4; ++m) _Pragma("unroll") for (int n = 0; n < 2; ++n) _Pragma("unroll") for (int k = 0; k < 2; ++k) \
;         acc[ai][bj][m][n] = __builtin_amdgcn_mfma_f32_16x16x32_bf16(Bt[n][k], At[m][k], acc[ai][bj][m][n], 0, 0, 0); __builtin_amdgcn_s_setprio(0); } while (0)
; #define PG8_WAIT_V(n) asm volatile("s_waitcnt vmcnt(" #n ")" ::: "memory")
; #define PG8_WAIT_L(n) asm volatile("s_waitcnt lgkmcnt(" #n ")" ::: "memory")
; #define PG8_BAR __builtin_amdgcn_s_barrier()
; #define PG8_SCHED __builtin_amdgcn_sched_barrier(0)
;     ...
;             PG8_WAIT_V(8); PG8_WAIT_L(0); PG8_BAR; PG8_MMA(1, 0, At, B0); PG8_MMA(1, 1, At, B1); PG8_BAR; PG8_SCHED;
;             PG8_LDB(B0, 1, 0); PG8_LDB(B1, 1, 1); PG8_SCHED; PG8_LDA(At, 1, 0); PG8_STAGE(PG8_SA(0, 1), a2 + hstep, voffA);
;             PG8_WAIT_V(8); PG8_WAIT_L(0); PG8_BAR; PG8_MMA(0, 0, At, B0); PG8_MMA(0, 1, At, B1); PG8_BAR; PG8_SCHED;
	s_setprio 1
	s_waitcnt lgkmcnt(0)
	v_mfma_f32_16x16x32_bf16 v[60:63], v[128:131], v[182:185], v[60:63]
	v_mfma_f32_16x16x32_bf16 v[56:59], v[136:139], v[182:185], v[56:59]
	v_mfma_f32_16x16x32_bf16 v[52:55], v[128:131], v[190:193], v[52:55]
	v_mfma_f32_16x16x32_bf16 v[48:51], v[136:139], v[190:193], v[48:51]
	v_mfma_f32_16x16x32_bf16 v[44:47], v[128:131], v[202:205], v[44:47]
	v_mfma_f32_16x16x32_bf16 v[40:43], v[136:139], v[202:205], v[40:43]
	v_mfma_f32_16x16x32_bf16 v[36:39], v[128:131], v[218:221], v[36:39]
	v_mfma_f32_16x16x32_bf16 v[32:35], v[136:139], v[218:221], v[32:35]
	v_mfma_f32_16x16x32_bf16 v[60:63], v[132:135], v[186:189], v[60:63]
	v_mfma_f32_16x16x32_bf16 v[56:59], v[140:143], v[186:189], v[56:59]
	v_mfma_f32_16x16x32_bf16 v[52:55], v[132:135], v[198:201], v[52:55]
	v_mfma_f32_16x16x32_bf16 v[48:51], v[140:143], v[198:201], v[48:51]
	v_mfma_f32_16x16x32_bf16 v[44:47], v[132:135], v[206:209], v[44:47]
	v_mfma_f32_16x16x32_bf16 v[40:43], v[140:143], v[206:209], v[40:43]
	v_mfma_f32_16x16x32_bf16 v[36:39], v[132:135], v[222:225], v[36:39]
	v_mfma_f32_16x16x32_bf16 v[32:35], v[140:143], v[222:225], v[32:35]
	s_setprio 0
	s_setprio 1
	v_mfma_f32_16x16x32_bf16 v[28:31], v[144:147], v[182:185], v[28:31]
	v_mfma_f32_16x16x32_bf16 v[24:27], v[152:155], v[182:185], v[24:27]
	v_mfma_f32_16x16x32_bf16 v[20:23], v[144:147], v[190:193], v[20:23]
	v_mfma_f32_16x16x32_bf16 v[16:19], v[152:155], v[190:193], v[16:19]
	v_mfma_f32_16x16x32_bf16 v[12:15], v[144:147], v[202:205], v[12:15]
	v_mfma_f32_16x16x32_bf16 v[8:11], v[152:155], v[202:205], v[8:11]
	v_mfma_f32_16x16x32_bf16 v[4:7], v[144:147], v[218:221], v[4:7]
	v_mfma_f32_16x16x32_bf16 v[0:3], v[152:155], v[218:221], v[0:3]
	v_mfma_f32_16x16x32_bf16 v[28:31], v[148:151], v[186:189], v[28:31]
	v_mfma_f32_16x16x32_bf16 v[24:27], v[156:159], v[186:189], v[24:27]
	v_mfma_f32_16x16x32_bf16 v[20:23], v[148:151], v[198:201], v[20:23]
	v_mfma_f32_16x16x32_bf16 v[16:19], v[156:159], v[198:201], v[16:19]
	v_mfma_f32_16x16x32_bf16 v[12:15], v[148:151], v[206:209], v[12:15]
	v_mfma_f32_16x16x32_bf16 v[8:11], v[156:159], v[206:209], v[8:11]
	v_mfma_f32_16x16x32_bf16 v[4:7], v[148:151], v[222:225], v[4:7]
	v_mfma_f32_16x16x32_bf16 v[0:3], v[156:159], v[222:225], v[0:3]
	s_setprio 0
	s_barrier
	s_add_i32 s53, 0, 0x18000
	s_add_i32 s90, 0, 0x1c000
	v_add_u32_e32 v140, s53, v195
	v_add_u32_e32 v156, s90, v195
	ds_read_b128 v[128:131], v140
	ds_read_b128 v[132:135], v140 offset:1024
	ds_read_b128 v[136:139], v140 offset:2048
	ds_read_b128 v[140:143], v140 offset:3072
	ds_read_b128 v[144:147], v156
	ds_read_b128 v[148:151], v156 offset:1024
	ds_read_b128 v[152:155], v156 offset:2048
	ds_read_b128 v[156:159], v156 offset:3072
	s_add_u32 s66, s66, 0x40000
	s_addc_u32 s67, s67, 0
	s_mov_b32 m0, s71
	v_lshl_add_u64 v[232:233], s[66:67], 0, v[160:161]
	ds_read_b128 v[182:185], v197 offset:32768
	ds_read_b128 v[186:189], v197 offset:33792
	ds_read_b128 v[190:193], v197 offset:34816
	ds_read_b128 v[198:201], v197 offset:35840
	ds_read_b128 v[202:205], v197 offset:36864
	ds_read_b128 v[206:209], v197 offset:37888
	ds_read_b128 v[218:221], v197 offset:38912
	ds_read_b128 v[222:225], v197 offset:39936
	global_load_lds_dwordx4 v[232:233], off
	v_lshl_add_u64 v[232:233], s[66:67], 0, v[162:163]
	s_mov_b32 m0, s72
	s_nop 0
	global_load_lds_dwordx4 v[232:233], off
	s_waitcnt vmcnt(8)
	s_waitcnt lgkmcnt(0)
	s_barrier
	s_setprio 1
	s_waitcnt lgkmcnt(0)
	v_mfma_f32_16x16x32_bf16 v[124:127], v[128:131], v[182:185], v[124:127]
	v_mfma_f32_16x16x32_bf16 v[120:123], v[136:139], v[182:185], v[120:123]
	v_mfma_f32_16x16x32_bf16 v[116:119], v[128:131], v[190:193], v[116:119]
	v_mfma_f32_16x16x32_bf16 v[112:115], v[136:139], v[190:193], v[112:115]
	v_mfma_f32_16x16x32_bf16 v[108:111], v[128:131], v[202:205], v[108:111]
	v_mfma_f32_16x16x32_bf16 v[104:107], v[136:139], v[202:205], v[104:107]
	v_mfma_f32_16x16x32_bf16 v[100:103], v[128:131], v[218:221], v[100:103]
	v_mfma_f32_16x16x32_bf16 v[96:99], v[136:139], v[218:221], v[96:99]
	v_mfma_f32_16x16x32_bf16 v[124:127], v[132:135], v[186:189], v[124:127]
	v_mfma_f32_16x16x32_bf16 v[120:123], v[140:143], v[186:189], v[120:123]
	v_mfma_f32_16x16x32_bf16 v[116:119], v[132:135], v[198:201], v[116:119]
	v_mfma_f32_16x16x32_bf16 v[112:115], v[140:143], v[198:201], v[112:115]
	v_mfma_f32_16x16x32_bf16 v[108:111], v[132:135], v[206:209], v[108:111]
	v_mfma_f32_16x16x32_bf16 v[104:107], v[140:143], v[206:209], v[104:107]
	v_mfma_f32_16x16x32_bf16 v[100:103], v[132:135], v[222:225], v[100:103]
	v_mfma_f32_16x16x32_bf16 v[96:99], v[140:143], v[222:225], v[96:99]
	s_setprio 0
	s_setprio 1
	v_mfma_f32_16x16x32_bf16 v[92:95], v[144:147], v[182:185], v[92:95]
	v_mfma_f32_16x16x32_bf16 v[88:91], v[152:155], v[182:185], v[88:91]
	v_mfma_f32_16x16x32_bf16 v[84:87], v[144:147], v[190:193], v[84:87]
	v_mfma_f32_16x16x32_bf16 v[80:83], v[152:155], v[190:193], v[80:83]
	v_mfma_f32_16x16x32_bf16 v[76:79], v[144:147], v[202:205], v[76:79]
	v_mfma_f32_16x16x32_bf16 v[72:75], v[152:155], v[202:205], v[72:75]
	v_mfma_f32_16x16x32_bf16 v[68:71], v[144:147], v[218:221], v[68:71]
	v_mfma_f32_16x16x32_bf16 v[64:67], v[152:155], v[218:221], v[64:67]
	v_mfma_f32_16x16x32_bf16 v[92:95], v[148:151], v[186:189], v[92:95]
	v_mfma_f32_16x16x32_bf16 v[88:91], v[156:159], v[186:189], v[88:91]
	v_mfma_f32_16x16x32_bf16 v[84:87], v[148:151], v[198:201], v[84:87]
	v_mfma_f32_16x16x32_bf16 v[80:83], v[156:159], v[198:201], v[80:83]
	v_mfma_f32_16x16x32_bf16 v[76:79], v[148:151], v[206:209], v[76:79]
	v_mfma_f32_16x16x32_bf16 v[72:75], v[156:159], v[206:209], v[72:75]
	v_mfma_f32_16x16x32_bf16 v[68:71], v[148:151], v[222:225], v[68:71]
	v_mfma_f32_16x16x32_bf16 v[64:67], v[156:159], v[222:225], v[64:67]
	s_setprio 0
	s_barrier
; #define GAS __attribute__((address_space(1)))
; #define PG8_STAGE(bufoff, gbase, voff) do { _Pragma("unroll") for (int _i = 0; _i < 2; ++_i) \
;         __builtin_amdgcn_global_load_lds((const GAS unsigned*)((const GAS char*)(gbase) + (voff)[_i]), (LAS unsigned*)(lds + (bufoff) + ldsw + _i * 8192), 16, 0, 0); } while (0)
; #define PG8_LDA(dst, b, h) do { _Pragma("unroll") for (int m = 0; m < 4; ++m) _Pragma("unroll") for (int k = 0; k < 2; ++k) dst[m][k] = *(const LAS bf16x8*)(lds + PG8_SA(b, h) + aoff + m * 2048 + k * 1024); } while (0)
; #define PG8_MMA(ai, bj, At, Bt) do { __builtin_amdgcn_s_setprio(1); _Pragma("unroll") for (int m = 0; m < 4; ++m) _Pragma("unroll") for (int n = 0; n < 2; ++n) _Pragma("unroll") for (int k = 0; k < 2; ++k) \
;         acc[ai][bj][m][n] = __builtin_amdgcn_mfma_f32_16x16x32_bf16(Bt[n][k], At[m][k], acc[ai][bj][m][n], 0, 0, 0); __builtin_amdgcn_s_setprio(0); } while (0)
; #define PG8_WAIT_V(n) asm volatile("s_waitcnt vmcnt(" #n ")" ::: "memory")
; #define PG8_WAIT_L(n) asm volatile("s_waitcnt lgkmcnt(" #n ")" ::: "memory")
; #define PG8_BAR __builtin_amdgcn_s_barrier()
; #define PG8_SCHED __builtin_amdgcn_sched_barrier(0)
;     ...
;         for (int t = 0; t < nt; t += 2) {
;             const bool last = (t == nt - 2);
;             const GAS char* a1 = cA + (size_t)(t + 1) * kstep;
;             const GAS char* a2 = last ? nA : cA + (size_t)(t + 2) * kstep; const GAS char* b2 = last ? nB : cB + (size_t)(t + 2) * kstep;
;             const GAS char* a3 = a2 + kstep; const GAS char* b3 = b2 + kstep;
;     ...
;             PG8_LDA(At, 1, 1); PG8_STAGE(PG8_SB(1, 0), b3, voffB); PG8_STAGE(PG8_SB(1, 1), b3 + hstep, voffB); PG8_STAGE(PG8_SA(1, 0), a3, voffA);
;             PG8_WAIT_V(8); PG8_WAIT_L(0); PG8_BAR; PG8_MMA(1, 0, At, B0); PG8_MMA(1, 1, At, B1); PG8_BAR; PG8_SCHED;
;         }
;         if (wr == 0) PG8_BAR;
	s_add_i32 s53, s53, s95
	v_lshl_add_u64 v[170:171], v[170:171], 0, s[82:83]
	s_mov_b32 m0, s53
	ds_read_b128 v[182:185], v197 offset:49152
	ds_read_b128 v[186:189], v197 offset:50176
	ds_read_b128 v[190:193], v197 offset:51200
	ds_read_b128 v[198:201], v197 offset:52224
	ds_read_b128 v[202:205], v197 offset:53248
	ds_read_b128 v[206:209], v197 offset:54272
	ds_read_b128 v[218:221], v197 offset:55296
	ds_read_b128 v[222:225], v197 offset:56320
	global_load_lds_dwordx4 v[170:171], off
	s_add_i32 m0, s53, 0x2000
	s_add_u32 s64, s64, 0x40080
	v_lshl_add_u64 v[170:171], v[226:227], 0, s[82:83]
	s_addc_u32 s65, s65, 0
	s_add_i32 s53, s90, s95
	global_load_lds_dwordx4 v[170:171], off
	v_lshl_add_u64 v[170:171], s[64:65], 0, v[172:173]
	s_mov_b32 m0, s53
	s_nop 0
	global_load_lds_dwordx4 v[170:171], off
	v_lshl_add_u64 v[170:171], s[64:65], 0, v[164:165]
	s_add_i32 m0, s53, 0x2000
	s_nop 0
	global_load_lds_dwordx4 v[170:171], off
	v_lshl_add_u64 v[170:171], v[228:229], 0, s[82:83]
	s_mov_b32 m0, s73
	s_nop 0
	global_load_lds_dwordx4 v[170:171], off
	v_lshl_add_u64 v[170:171], v[230:231], 0, s[82:83]
	s_mov_b32 m0, s74
	s_nop 0
	global_load_lds_dwordx4 v[170:171], off
	s_waitcnt vmcnt(8)
	s_waitcnt lgkmcnt(0)
	s_barrier
	s_setprio 1
	s_waitcnt lgkmcnt(0)
	v_mfma_f32_16x16x32_bf16 v[60:63], v[128:131], v[182:185], v[60:63]
	v_mfma_f32_16x16x32_bf16 v[56:59], v[136:139], v[182:185], v[56:59]
	v_mfma_f32_16x16x32_bf16 v[52:55], v[128:131], v[190:193], v[52:55]
	v_mfma_f32_16x16x32_bf16 v[48:51], v[136:139], v[190:193], v[48:51]
	v_mfma_f32_16x16x32_bf16 v[44:47], v[128:131], v[202:205], v[44:47]
	v_mfma_f32_16x16x32_bf16 v[40:43], v[136:139], v[202:205], v[40:43]
	v_mfma_f32_16x16x32_bf16 v[36:39], v[128:131], v[218:221], v[36:39]
	v_mfma_f32_16x16x32_bf16 v[32:35], v[136:139], v[218:221], v[32:35]
	v_mfma_f32_16x16x32_bf16 v[60:63], v[132:135], v[186:189], v[60:63]
	v_mfma_f32_16x16x32_bf16 v[56:59], v[140:143], v[186:189], v[56:59]
	v_mfma_f32_16x16x32_bf16 v[52:55], v[132:135], v[198:201], v[52:55]
	v_mfma_f32_16x16x32_bf16 v[48:51], v[140:143], v[198:201], v[48:51]
	v_mfma_f32_16x16x32_bf16 v[44:47], v[132:135], v[206:209], v[44:47]
	v_mfma_f32_16x16x32_bf16 v[40:43], v[140:143], v[206:209], v[40:43]
	v_mfma_f32_16x16x32_bf16 v[36:39], v[132:135], v[222:225], v[36:39]
	v_mfma_f32_16x16x32_bf16 v[32:35], v[140:143], v[222:225], v[32:35]
	s_setprio 0
	s_setprio 1
	v_mfma_f32_16x16x32_bf16 v[28:31], v[144:147], v[182:185], v[28:31]
	v_mfma_f32_16x16x32_bf16 v[24:27], v[152:155], v[182:185], v[24:27]
	v_mfma_f32_16x16x32_bf16 v[20:23], v[144:147], v[190:193], v[20:23]
	v_mfma_f32_16x16x32_bf16 v[16:19], v[152:155], v[190:193], v[16:19]
	v_mfma_f32_16x16x32_bf16 v[12:15], v[144:147], v[202:205], v[12:15]
	v_mfma_f32_16x16x32_bf16 v[8:11], v[152:155], v[202:205], v[8:11]
	v_mfma_f32_16x16x32_bf16 v[4:7], v[144:147], v[218:221], v[4:7]
	v_mfma_f32_16x16x32_bf16 v[0:3], v[152:155], v[218:221], v[0:3]
	v_mfma_f32_16x16x32_bf16 v[28:31], v[148:151], v[186:189], v[28:31]
	v_mfma_f32_16x16x32_bf16 v[24:27], v[156:159], v[186:189], v[24:27]
	v_mfma_f32_16x16x32_bf16 v[20:23], v[148:151], v[198:201], v[20:23]
	v_mfma_f32_16x16x32_bf16 v[16:19], v[156:159], v[198:201], v[16:19]
	v_mfma_f32_16x16x32_bf16 v[12:15], v[148:151], v[206:209], v[12:15]
	v_mfma_f32_16x16x32_bf16 v[8:11], v[156:159], v[206:209], v[8:11]
	v_mfma_f32_16x16x32_bf16 v[4:7], v[148:151], v[222:225], v[4:7]
	v_mfma_f32_16x16x32_bf16 v[0:3], v[156:159], v[222:225], v[0:3]
	s_setprio 0
	s_add_i32 s25, s25, 2
	s_add_u32 s13, s13, 0x100
	s_addc_u32 s17, s17, 0
	s_add_u32 s62, s62, 0x100
	s_addc_u32 s63, s63, 0
	s_cmp_gt_u32 s25, 13
	s_cbranch_scc1 .Lrot_exit_m
	s_add_u32 s53, s62, 0xfffc0080
	s_addc_u32 s64, s63, -1
	s_add_i32 s90, 0, 0x10000
	s_cmp_eq_u32 s25, 12
	s_cselect_b32 s67, s27, s64
	s_cselect_b32 s66, s26, s53
	s_cselect_b32 s65, s37, s17
	s_cselect_b32 s64, s36, s13
	s_add_i32 s53, 0, 0x14000
	s_branch .Lrot_head_m
.Lrot_exit_m:
	s_barrier
	v_readlane_b32 s62, v243, 62
	v_readlane_b32 s63, v243, 63
	s_and_b64 vcc, exec, s[62:63]
	s_cbranch_vccz .LBB0_960
	s_barrier

; #define GAS __attribute__((address_space(1)))
;     ...
;         for (int t = 0; t < nt; t += 2) {
;             const bool last = (t == nt - 2);
;             const GAS char* a1 = cA + (size_t)(t + 1) * kstep;
;             const GAS char* a2 = last ? nA : cA + (size_t)(t + 2) * kstep; const GAS char* b2 = last ? nB : cB + (size_t)(t + 2) * kstep;
;             const GAS char* a3 = a2 + kstep; const GAS char* b3 = b2 + kstep;
.LBB0_1187:
	s_add_u32 s64, s62, 0xfffc0080
	s_addc_u32 s65, s63, -1
	s_add_i32 s93, 0, 0x10000
	s_cmp_eq_u32 s92, 12
	s_cselect_b32 s67, s17, s65
	s_cselect_b32 s66, s53, s64
	s_cselect_b32 s65, s15, s91
	s_cselect_b32 s64, s61, s90
	s_add_i32 s56, 0, 0x14000
	s_branch .Lrot_body_o

; #define PG8_STAGE(bufoff, gbase, voff) do { _Pragma("unroll") for (int _i = 0; _i < 2; ++_i) \
;         __builtin_amdgcn_global_load_lds((const GAS unsigned*)((const GAS char*)(gbase) + (voff)[_i]), (LAS unsigned*)(lds + (bufoff) + ldsw + _i * 8192), 16, 0, 0); } while (0)
; #define PG8_LDA(dst, b, h) do { _Pragma("unroll") for (int m = 0; m < 4; ++m) _Pragma("unroll") for (int k = 0; k < 2; ++k) dst[m][k] = *(const LAS bf16x8*)(lds + PG8_SA(b, h) + aoff + m * 2048 + k * 1024); } while (0)
; #define PG8_LDB(dst, b, h) do { _Pragma("unroll") for (int n = 0; n < 2; ++n) _Pragma("unroll") for (int k = 0; k < 2; ++k) dst[n][k] = *(const LAS bf16x8*)(lds + PG8_SB(b, h) + boff + n * 2048 + k * 1024); } while (0)
; #define PG8_MMA(ai, bj, At, Bt) do { __builtin_amdgcn_s_setprio(1); _Pragma("unroll") for (int m = 0; m < 4; ++m) _Pragma("unroll") for (int n = 0; n < 2; ++n) _Pragma("unroll") for (int k = 0; k < 2; ++k) \
;         acc[ai][bj][m][n] = __builtin_amdgcn_mfma_f32_16x16x32_bf16(Bt[n][k], At[m][k], acc[ai][bj][m][n], 0, 0, 0); __builtin_amdgcn_s_setprio(0); } while (0)
; #define PG8_WAIT_V(n) asm volatile("s_waitcnt vmcnt(" #n ")" ::: "memory")
; #define PG8_WAIT_L(n) asm volatile("s_waitcnt lgkmcnt(" #n ")" ::: "memory")
; #define PG8_BAR __builtin_amdgcn_s_barrier()
; #define PG8_SCHED __builtin_amdgcn_sched_barrier(0)
;     ...
;             PG8_LDB(B0, 0, 0); PG8_LDB(B1, 0, 1); PG8_SCHED; PG8_LDA(At, 0, 0); PG8_STAGE(PG8_SA(1, 1), a1 + hstep, voffA);
;             PG8_WAIT_V(8); PG8_WAIT_L(0); PG8_BAR; PG8_MMA(0, 0, At, B0); PG8_MMA(0, 1, At, B1); PG8_BAR; PG8_SCHED;
;             PG8_LDA(At, 0, 1); PG8_STAGE(PG8_SB(0, 0), b2, voffB); PG8_STAGE(PG8_SB(0, 1), b2 + hstep, voffB); PG8_STAGE(PG8_SA(0, 0), a2, voffA);
;             PG8_WAIT_V(8); PG8_WAIT_L(0); PG8_BAR; PG8_MMA(1, 0, At, B0); PG8_MMA(1, 1, At, B1); PG8_BAR; PG8_SCHED;
.Lrot_body_o:
	v_add_u32_e32 v140, s93, v203
	v_add_u32_e32 v156, s56, v203
	ds_read_b128 v[128:131], v140
	ds_read_b128 v[132:135], v140 offset:1024
	ds_read_b128 v[136:139], v140 offset:2048
	ds_read_b128 v[140:143], v140 offset:3072
	ds_read_b128 v[144:147], v156
	ds_read_b128 v[148:151], v156 offset:1024
	ds_read_b128 v[152:155], v156 offset:2048
	ds_read_b128 v[156:159], v156 offset:3072
	v_lshl_add_u64 v[170:171], s[62:63], 0, v[168:169]
	s_add_i32 m0, s71, 0xc000
	ds_read_b128 v[182:185], v205
	ds_read_b128 v[186:189], v205 offset:1024
	ds_read_b128 v[190:193], v205 offset:2048
	ds_read_b128 v[194:197], v205 offset:3072
	ds_read_b128 v[198:201], v205 offset:4096
	ds_read_b128 v[206:209], v205 offset:5120
	ds_read_b128 v[218:221], v205 offset:6144
	ds_read_b128 v[222:225], v205 offset:7168
	global_load_lds_dwordx4 v[170:171], off
	v_lshl_add_u64 v[170:171], s[62:63], 0, v[166:167]
	s_add_i32 m0, s71, 0xe000
	s_nop 0
	global_load_lds_dwordx4 v[170:171], off
	s_waitcnt vmcnt(8)
	s_waitcnt lgkmcnt(0)
	s_barrier
	s_setprio 1
	s_waitcnt lgkmcnt(0)
	v_mfma_f32_16x16x32_bf16 v[124:127], v[128:131], v[182:185], v[124:127]
	v_mfma_f32_16x16x32_bf16 v[120:123], v[136:139], v[182:185], v[120:123]
	v_mfma_f32_16x16x32_bf16 v[108:111], v[128:131], v[190:193], v[108:111]
	v_mfma_f32_16x16x32_bf16 v[104:107], v[136:139], v[190:193], v[104:107]
	v_mfma_f32_16x16x32_bf16 v[92:95], v[128:131], v[198:201], v[92:95]
	v_mfma_f32_16x16x32_bf16 v[88:91], v[136:139], v[198:201], v[88:91]
	v_mfma_f32_16x16x32_bf16 v[76:79], v[128:131], v[218:221], v[76:79]
	v_mfma_f32_16x16x32_bf16 v[72:75], v[136:139], v[218:221], v[72:75]
	v_mfma_f32_16x16x32_bf16 v[124:127], v[132:135], v[186:189], v[124:127]
	v_mfma_f32_16x16x32_bf16 v[120:123], v[140:143], v[186:189], v[120:123]
	v_mfma_f32_16x16x32_bf16 v[108:111], v[132:135], v[194:197], v[108:111]
	v_mfma_f32_16x16x32_bf16 v[104:107], v[140:143], v[194:197], v[104:107]
	v_mfma_f32_16x16x32_bf16 v[92:95], v[132:135], v[206:209], v[92:95]
	v_mfma_f32_16x16x32_bf16 v[88:91], v[140:143], v[206:209], v[88:91]
	v_mfma_f32_16x16x32_bf16 v[76:79], v[132:135], v[222:225], v[76:79]
	v_mfma_f32_16x16x32_bf16 v[72:75], v[140:143], v[222:225], v[72:75]
	s_setprio 0
	s_setprio 1
	v_mfma_f32_16x16x32_bf16 v[116:119], v[144:147], v[182:185], v[116:119]
	v_mfma_f32_16x16x32_bf16 v[112:115], v[152:155], v[182:185], v[112:115]
	v_mfma_f32_16x16x32_bf16 v[100:103], v[144:147], v[190:193], v[100:103]
	v_mfma_f32_16x16x32_bf16 v[96:99], v[152:155], v[190:193], v[96:99]
	v_mfma_f32_16x16x32_bf16 v[84:87], v[144:147], v[198:201], v[84:87]
	v_mfma_f32_16x16x32_bf16 v[80:83], v[152:155], v[198:201], v[80:83]
	v_mfma_f32_16x16x32_bf16 v[68:71], v[144:147], v[218:221], v[68:71]
	v_mfma_f32_16x16x32_bf16 v[64:67], v[152:155], v[218:221], v[64:67]
	v_mfma_f32_16x16x32_bf16 v[116:119], v[148:151], v[186:189], v[116:119]
	v_mfma_f32_16x16x32_bf16 v[112:115], v[156:159], v[186:189], v[112:115]
	v_mfma_f32_16x16x32_bf16 v[100:103], v[148:151], v[194:197], v[100:103]
	v_mfma_f32_16x16x32_bf16 v[96:99], v[156:159], v[194:197], v[96:99]
	v_mfma_f32_16x16x32_bf16 v[84:87], v[148:151], v[206:209], v[84:87]
	v_mfma_f32_16x16x32_bf16 v[80:83], v[156:159], v[206:209], v[80:83]
	v_mfma_f32_16x16x32_bf16 v[68:71], v[148:151], v[222:225], v[68:71]
	v_mfma_f32_16x16x32_bf16 v[64:67], v[156:159], v[222:225], v[64:67]
	s_setprio 0
	s_barrier
	s_add_i32 s57, s93, s95
	v_lshl_add_u64 v[170:171], s[64:65], 0, v[172:173]
	s_mov_b32 m0, s57
	ds_read_b128 v[182:185], v205 offset:16384
	ds_read_b128 v[186:189], v205 offset:17408
	ds_read_b128 v[190:193], v205 offset:18432
	ds_read_b128 v[194:197], v205 offset:19456
	ds_read_b128 v[198:201], v205 offset:20480
	ds_read_b128 v[206:209], v205 offset:21504
	ds_read_b128 v[218:221], v205 offset:22528
	ds_read_b128 v[222:225], v205 offset:23552
	global_load_lds_dwordx4 v[170:171], off
	s_add_i32 m0, s57, 0x2000
	s_add_u32 vcc_lo, s64, 0x40000
	v_lshl_add_u64 v[226:227], s[64:65], 0, v[164:165]
	s_addc_u32 vcc_hi, s65, 0
	s_add_i32 s56, s56, s95
	global_load_lds_dwordx4 v[226:227], off
	v_lshl_add_u64 v[228:229], vcc, 0, v[172:173]
	s_mov_b32 m0, s56
	v_lshl_add_u64 v[230:231], s[66:67], 0, v[162:163]
	global_load_lds_dwordx4 v[228:229], off
	v_lshl_add_u64 v[228:229], vcc, 0, v[164:165]
	s_add_i32 m0, s56, 0x2000
	s_nop 0
	global_load_lds_dwordx4 v[228:229], off
	v_lshl_add_u64 v[228:229], s[66:67], 0, v[160:161]
	s_mov_b32 m0, s71
	s_nop 0
	global_load_lds_dwordx4 v[228:229], off
	s_mov_b32 m0, s72
	s_nop 0
	global_load_lds_dwordx4 v[230:231], off
	s_waitcnt vmcnt(8)
	s_waitcnt lgkmcnt(0)
	s_barrier
; #define PG8_STAGE(bufoff, gbase, voff) do { _Pragma("unroll") for (int _i = 0; _i < 2; ++_i) \
;         __builtin_amdgcn_global_load_lds((const GAS unsigned*)((const GAS char*)(gbase) + (voff)[_i]), (LAS unsigned*)(lds + (bufoff) + ldsw + _i * 8192), 16, 0, 0); } while (0)
; #define PG8_LDA(dst, b, h) do { _Pragma("unroll") for (int m = 0; m < 4; ++m) _Pragma("unroll") for (int k = 0; k < 2; ++k) dst[m][k] = *(const LAS bf16x8*)(lds + PG8_SA(b, h) + aoff + m * 2048 + k * 1024); } while (0)
; #define PG8_LDB(dst, b, h) do { _Pragma("unroll") for (int n = 0; n < 2; ++n) _Pragma("unroll") for (int k = 0; k < 2; ++k) dst[n][k] = *(const LAS bf16x8*)(lds + PG8_SB(b, h) + boff + n * 2048 + k * 1024); } while (0)
; #define PG8_MMA(ai, bj, At, Bt) do { __builtin_amdgcn_s_setprio(1); _Pragma("unroll") for (int m = 0; m < 4; ++m) _Pragma("unroll") for (int n = 0; n < 2; ++n) _Pragma("unroll") for (int k = 0; k < 2; ++k) \
;         acc[ai][bj][m][n] = __builtin_amdgcn_mfma_f32_16x16x32_bf16(Bt[n][k], At[m][k], acc[ai][bj][m][n], 0, 0, 0); __builtin_amdgcn_s_setprio(0); } while (0)
; #define PG8_WAIT_V(n) asm volatile("s_waitcnt vmcnt(" #n ")" ::: "memory")
; #define PG8_WAIT_L(n) asm volatile("s_waitcnt lgkmcnt(" #n ")" ::: "memory")
; #define PG8_BAR __builtin_amdgcn_s_barrier()
; #define PG8_SCHED __builtin_amdgcn_sched_barrier(0)
;     ...
;             PG8_WAIT_V(8); PG8_WAIT_L(0); PG8_BAR; PG8_MMA(1, 0, At, B0); PG8_MMA(1, 1, At, B1); PG8_BAR; PG8_SCHED;
;             PG8_LDB(B0, 1, 0); PG8_LDB(B1, 1, 1); PG8_SCHED; PG8_LDA(At, 1, 0); PG8_STAGE(PG8_SA(0, 1), a2 + hstep, voffA);
;             PG8_WAIT_V(8); PG8_WAIT_L(0); PG8_BAR; PG8_MMA(0, 0, At, B0); PG8_MMA(0, 1, At, B1); PG8_BAR; PG8_SCHED;
	s_setprio 1
	s_waitcnt lgkmcnt(0)
	v_mfma_f32_16x16x32_bf16 v[60:63], v[128:131], v[182:185], v[60:63]
	v_mfma_f32_16x16x32_bf16 v[56:59], v[136:139], v[182:185], v[56:59]
	v_mfma_f32_16x16x32_bf16 v[44:47], v[128:131], v[190:193], v[44:47]
	v_mfma_f32_16x16x32_bf16 v[40:43], v[136:139], v[190:193], v[40:43]
	v_mfma_f32_16x16x32_bf16 v[28:31], v[128:131], v[198:201], v[28:31]
	v_mfma_f32_16x16x32_bf16 v[24:27], v[136:139], v[198:201], v[24:27]
	v_mfma_f32_16x16x32_bf16 v[12:15], v[128:131], v[218:221], v[12:15]
	v_mfma_f32_16x16x32_bf16 v[8:11], v[136:139], v[218:221], v[8:11]
	v_mfma_f32_16x16x32_bf16 v[60:63], v[132:135], v[186:189], v[60:63]
	v_mfma_f32_16x16x32_bf16 v[56:59], v[140:143], v[186:189], v[56:59]
	v_mfma_f32_16x16x32_bf16 v[44:47], v[132:135], v[194:197], v[44:47]
	v_mfma_f32_16x16x32_bf16 v[40:43], v[140:143], v[194:197], v[40:43]
	v_mfma_f32_16x16x32_bf16 v[28:31], v[132:135], v[206:209], v[28:31]
	v_mfma_f32_16x16x32_bf16 v[24:27], v[140:143], v[206:209], v[24:27]
	v_mfma_f32_16x16x32_bf16 v[12:15], v[132:135], v[222:225], v[12:15]
	v_mfma_f32_16x16x32_bf16 v[8:11], v[140:143], v[222:225], v[8:11]
	s_setprio 0
	s_setprio 1
	v_mfma_f32_16x16x32_bf16 v[52:55], v[144:147], v[182:185], v[52:55]
	v_mfma_f32_16x16x32_bf16 v[48:51], v[152:155], v[182:185], v[48:51]
	v_mfma_f32_16x16x32_bf16 v[36:39], v[144:147], v[190:193], v[36:39]
	v_mfma_f32_16x16x32_bf16 v[32:35], v[152:155], v[190:193], v[32:35]
	v_mfma_f32_16x16x32_bf16 v[20:23], v[144:147], v[198:201], v[20:23]
	v_mfma_f32_16x16x32_bf16 v[16:19], v[152:155], v[198:201], v[16:19]
	v_mfma_f32_16x16x32_bf16 v[4:7], v[144:147], v[218:221], v[4:7]
	v_mfma_f32_16x16x32_bf16 v[0:3], v[152:155], v[218:221], v[0:3]
	v_mfma_f32_16x16x32_bf16 v[52:55], v[148:151], v[186:189], v[52:55]
	v_mfma_f32_16x16x32_bf16 v[48:51], v[156:159], v[186:189], v[48:51]
	v_mfma_f32_16x16x32_bf16 v[36:39], v[148:151], v[194:197], v[36:39]
	v_mfma_f32_16x16x32_bf16 v[32:35], v[156:159], v[194:197], v[32:35]
	v_mfma_f32_16x16x32_bf16 v[20:23], v[148:151], v[206:209], v[20:23]
	v_mfma_f32_16x16x32_bf16 v[16:19], v[156:159], v[206:209], v[16:19]
	v_mfma_f32_16x16x32_bf16 v[4:7], v[148:151], v[222:225], v[4:7]
	v_mfma_f32_16x16x32_bf16 v[0:3], v[156:159], v[222:225], v[0:3]
	s_setprio 0
	s_barrier
	s_add_i32 s56, 0, 0x18000
	s_add_i32 s57, 0, 0x1c000
	v_add_u32_e32 v140, s56, v203
	v_add_u32_e32 v156, s57, v203
	ds_read_b128 v[128:131], v140
	ds_read_b128 v[132:135], v140 offset:1024
	ds_read_b128 v[136:139], v140 offset:2048
	ds_read_b128 v[140:143], v140 offset:3072
	ds_read_b128 v[144:147], v156
	ds_read_b128 v[148:151], v156 offset:1024
	ds_read_b128 v[152:155], v156 offset:2048
	ds_read_b128 v[156:159], v156 offset:3072
	s_add_u32 s66, s66, 0x40000
	s_addc_u32 s67, s67, 0
	s_mov_b32 m0, s73
	v_lshl_add_u64 v[232:233], s[66:67], 0, v[160:161]
	ds_read_b128 v[182:185], v205 offset:32768
	ds_read_b128 v[186:189], v205 offset:33792
	ds_read_b128 v[190:193], v205 offset:34816
	ds_read_b128 v[194:197], v205 offset:35840
	ds_read_b128 v[198:201], v205 offset:36864
	ds_read_b128 v[206:209], v205 offset:37888
	ds_read_b128 v[218:221], v205 offset:38912
	ds_read_b128 v[222:225], v205 offset:39936
	global_load_lds_dwordx4 v[232:233], off
	v_lshl_add_u64 v[232:233], s[66:67], 0, v[162:163]
	s_mov_b32 m0, s74
	s_nop 0
	global_load_lds_dwordx4 v[232:233], off
	s_waitcnt vmcnt(8)
	s_waitcnt lgkmcnt(0)
	s_barrier
	s_setprio 1
	s_waitcnt lgkmcnt(0)
	v_mfma_f32_16x16x32_bf16 v[124:127], v[128:131], v[182:185], v[124:127]
	v_mfma_f32_16x16x32_bf16 v[120:123], v[136:139], v[182:185], v[120:123]
	v_mfma_f32_16x16x32_bf16 v[108:111], v[128:131], v[190:193], v[108:111]
	v_mfma_f32_16x16x32_bf16 v[104:107], v[136:139], v[190:193], v[104:107]
	v_mfma_f32_16x16x32_bf16 v[92:95], v[128:131], v[198:201], v[92:95]
	v_mfma_f32_16x16x32_bf16 v[88:91], v[136:139], v[198:201], v[88:91]
	v_mfma_f32_16x16x32_bf16 v[76:79], v[128:131], v[218:221], v[76:79]
	v_mfma_f32_16x16x32_bf16 v[72:75], v[136:139], v[218:221], v[72:75]
	v_mfma_f32_16x16x32_bf16 v[124:127], v[132:135], v[186:189], v[124:127]
	v_mfma_f32_16x16x32_bf16 v[120:123], v[140:143], v[186:189], v[120:123]
	v_mfma_f32_16x16x32_bf16 v[108:111], v[132:135], v[194:197], v[108:111]
	v_mfma_f32_16x16x32_bf16 v[104:107], v[140:143], v[194:197], v[104:107]
	v_mfma_f32_16x16x32_bf16 v[92:95], v[132:135], v[206:209], v[92:95]
	v_mfma_f32_16x16x32_bf16 v[88:91], v[140:143], v[206:209], v[88:91]
	v_mfma_f32_16x16x32_bf16 v[76:79], v[132:135], v[222:225], v[76:79]
	v_mfma_f32_16x16x32_bf16 v[72:75], v[140:143], v[222:225], v[72:75]
	s_setprio 0
	s_setprio 1
	v_mfma_f32_16x16x32_bf16 v[116:119], v[144:147], v[182:185], v[116:119]
	v_mfma_f32_16x16x32_bf16 v[112:115], v[152:155], v[182:185], v[112:115]
	v_mfma_f32_16x16x32_bf16 v[100:103], v[144:147], v[190:193], v[100:103]
	v_mfma_f32_16x16x32_bf16 v[96:99], v[152:155], v[190:193], v[96:99]
	v_mfma_f32_16x16x32_bf16 v[84:87], v[144:147], v[198:201], v[84:87]
	v_mfma_f32_16x16x32_bf16 v[80:83], v[152:155], v[198:201], v[80:83]
	v_mfma_f32_16x16x32_bf16 v[68:71], v[144:147], v[218:221], v[68:71]
	v_mfma_f32_16x16x32_bf16 v[64:67], v[152:155], v[218:221], v[64:67]
	v_mfma_f32_16x16x32_bf16 v[116:119], v[148:151], v[186:189], v[116:119]
	v_mfma_f32_16x16x32_bf16 v[112:115], v[156:159], v[186:189], v[112:115]
	v_mfma_f32_16x16x32_bf16 v[100:103], v[148:151], v[194:197], v[100:103]
	v_mfma_f32_16x16x32_bf16 v[96:99], v[156:159], v[194:197], v[96:99]
	v_mfma_f32_16x16x32_bf16 v[84:87], v[148:151], v[206:209], v[84:87]
	v_mfma_f32_16x16x32_bf16 v[80:83], v[156:159], v[206:209], v[80:83]
	v_mfma_f32_16x16x32_bf16 v[68:71], v[148:151], v[222:225], v[68:71]
	v_mfma_f32_16x16x32_bf16 v[64:67], v[156:159], v[222:225], v[64:67]
	s_setprio 0
	s_barrier
; #define GAS __attribute__((address_space(1)))
; #define PG8_STAGE(bufoff, gbase, voff) do { _Pragma("unroll") for (int _i = 0; _i < 2; ++_i) \
;         __builtin_amdgcn_global_load_lds((const GAS unsigned*)((const GAS char*)(gbase) + (voff)[_i]), (LAS unsigned*)(lds + (bufoff) + ldsw + _i * 8192), 16, 0, 0); } while (0)
; #define PG8_LDA(dst, b, h) do { _Pragma("unroll") for (int m = 0; m < 4; ++m) _Pragma("unroll") for (int k = 0; k < 2; ++k) dst[m][k] = *(const LAS bf16x8*)(lds + PG8_SA(b, h) + aoff + m * 2048 + k * 1024); } while (0)
; #define PG8_MMA(ai, bj, At, Bt) do { __builtin_amdgcn_s_setprio(1); _Pragma("unroll") for (int m = 0; m < 4; ++m) _Pragma("unroll") for (int n = 0; n < 2; ++n) _Pragma("unroll") for (int k = 0; k < 2; ++k) \
;         acc[ai][bj][m][n] = __builtin_amdgcn_mfma_f32_16x16x32_bf16(Bt[n][k], At[m][k], acc[ai][bj][m][n], 0, 0, 0); __builtin_amdgcn_s_setprio(0); } while (0)
; #define PG8_WAIT_V(n) asm volatile("s_waitcnt vmcnt(" #n ")" ::: "memory")
; #define PG8_WAIT_L(n) asm volatile("s_waitcnt lgkmcnt(" #n ")" ::: "memory")
; #define PG8_BAR __builtin_amdgcn_s_barrier()
; #define PG8_SCHED __builtin_amdgcn_sched_barrier(0)
;     ...
;         for (int t = 0; t < nt; t += 2) {
;             const bool last = (t == nt - 2);
;             const GAS char* a1 = cA + (size_t)(t + 1) * kstep;
;             const GAS char* a2 = last ? nA : cA + (size_t)(t + 2) * kstep; const GAS char* b2 = last ? nB : cB + (size_t)(t + 2) * kstep;
;             const GAS char* a3 = a2 + kstep; const GAS char* b3 = b2 + kstep;
;     ...
;             PG8_LDA(At, 1, 1); PG8_STAGE(PG8_SB(1, 0), b3, voffB); PG8_STAGE(PG8_SB(1, 1), b3 + hstep, voffB); PG8_STAGE(PG8_SA(1, 0), a3, voffA);
;             PG8_WAIT_V(8); PG8_WAIT_L(0); PG8_BAR; PG8_MMA(1, 0, At, B0); PG8_MMA(1, 1, At, B1); PG8_BAR; PG8_SCHED;
;         }
;         if (wr == 0) PG8_BAR;
	s_add_i32 s56, s56, s95
	v_lshl_add_u64 v[170:171], v[170:171], 0, s[82:83]
	s_mov_b32 m0, s56
	ds_read_b128 v[182:185], v205 offset:49152
	ds_read_b128 v[186:189], v205 offset:50176
	ds_read_b128 v[190:193], v205 offset:51200
	ds_read_b128 v[194:197], v205 offset:52224
	ds_read_b128 v[198:201], v205 offset:53248
	ds_read_b128 v[206:209], v205 offset:54272
	ds_read_b128 v[218:221], v205 offset:55296
	ds_read_b128 v[222:225], v205 offset:56320
	global_load_lds_dwordx4 v[170:171], off
	s_add_i32 m0, s56, 0x2000
	s_add_u32 s64, s64, 0x40080
	v_lshl_add_u64 v[170:171], v[226:227], 0, s[82:83]
	s_addc_u32 s65, s65, 0
	s_add_i32 s56, s57, s95
	global_load_lds_dwordx4 v[170:171], off
	v_lshl_add_u64 v[170:171], s[64:65], 0, v[172:173]
	s_mov_b32 m0, s56
	s_nop 0
	global_load_lds_dwordx4 v[170:171], off
	v_lshl_add_u64 v[170:171], s[64:65], 0, v[164:165]
	s_add_i32 m0, s56, 0x2000
	s_nop 0
	global_load_lds_dwordx4 v[170:171], off
	v_lshl_add_u64 v[170:171], v[228:229], 0, s[82:83]
	s_mov_b32 m0, s75
	s_nop 0
	global_load_lds_dwordx4 v[170:171], off
	v_lshl_add_u64 v[170:171], v[230:231], 0, s[82:83]
	s_mov_b32 m0, s88
	s_nop 0
	global_load_lds_dwordx4 v[170:171], off
	s_waitcnt vmcnt(8)
	s_waitcnt lgkmcnt(0)
	s_barrier
	s_setprio 1
	s_waitcnt lgkmcnt(0)
	v_mfma_f32_16x16x32_bf16 v[60:63], v[128:131], v[182:185], v[60:63]
	v_mfma_f32_16x16x32_bf16 v[56:59], v[136:139], v[182:185], v[56:59]
	v_mfma_f32_16x16x32_bf16 v[44:47], v[128:131], v[190:193], v[44:47]
	v_mfma_f32_16x16x32_bf16 v[40:43], v[136:139], v[190:193], v[40:43]
	v_mfma_f32_16x16x32_bf16 v[28:31], v[128:131], v[198:201], v[28:31]
	v_mfma_f32_16x16x32_bf16 v[24:27], v[136:139], v[198:201], v[24:27]
	v_mfma_f32_16x16x32_bf16 v[12:15], v[128:131], v[218:221], v[12:15]
	v_mfma_f32_16x16x32_bf16 v[8:11], v[136:139], v[218:221], v[8:11]
	v_mfma_f32_16x16x32_bf16 v[60:63], v[132:135], v[186:189], v[60:63]
	v_mfma_f32_16x16x32_bf16 v[56:59], v[140:143], v[186:189], v[56:59]
	v_mfma_f32_16x16x32_bf16 v[44:47], v[132:135], v[194:197], v[44:47]
	v_mfma_f32_16x16x32_bf16 v[40:43], v[140:143], v[194:197], v[40:43]
	v_mfma_f32_16x16x32_bf16 v[28:31], v[132:135], v[206:209], v[28:31]
	v_mfma_f32_16x16x32_bf16 v[24:27], v[140:143], v[206:209], v[24:27]
	v_mfma_f32_16x16x32_bf16 v[12:15], v[132:135], v[222:225], v[12:15]
	v_mfma_f32_16x16x32_bf16 v[8:11], v[140:143], v[222:225], v[8:11]
	s_setprio 0
	s_setprio 1
	v_mfma_f32_16x16x32_bf16 v[52:55], v[144:147], v[182:185], v[52:55]
	v_mfma_f32_16x16x32_bf16 v[48:51], v[152:155], v[182:185], v[48:51]
	v_mfma_f32_16x16x32_bf16 v[36:39], v[144:147], v[190:193], v[36:39]
	v_mfma_f32_16x16x32_bf16 v[32:35], v[152:155], v[190:193], v[32:35]
	v_mfma_f32_16x16x32_bf16 v[20:23], v[144:147], v[198:201], v[20:23]
	v_mfma_f32_16x16x32_bf16 v[16:19], v[152:155], v[198:201], v[16:19]
	v_mfma_f32_16x16x32_bf16 v[4:7], v[144:147], v[218:221], v[4:7]
	v_mfma_f32_16x16x32_bf16 v[0:3], v[152:155], v[218:221], v[0:3]
	v_mfma_f32_16x16x32_bf16 v[52:55], v[148:151], v[186:189], v[52:55]
	v_mfma_f32_16x16x32_bf16 v[48:51], v[156:159], v[186:189], v[48:51]
	v_mfma_f32_16x16x32_bf16 v[36:39], v[148:151], v[194:197], v[36:39]
	v_mfma_f32_16x16x32_bf16 v[32:35], v[156:159], v[194:197], v[32:35]
	v_mfma_f32_16x16x32_bf16 v[20:23], v[148:151], v[206:209], v[20:23]
	v_mfma_f32_16x16x32_bf16 v[16:19], v[156:159], v[206:209], v[16:19]
	v_mfma_f32_16x16x32_bf16 v[4:7], v[148:151], v[222:225], v[4:7]
	v_mfma_f32_16x16x32_bf16 v[0:3], v[156:159], v[222:225], v[0:3]
	s_setprio 0
	s_add_i32 s92, s92, 2
	s_add_u32 s90, s90, 0x100
	s_addc_u32 s91, s91, 0
	s_add_u32 s62, s62, 0x100
	s_addc_u32 s63, s63, 0
	s_cmp_gt_u32 s92, 13
	s_cbranch_scc1 .Lrot_exit_o
	s_add_u32 s64, s62, 0xfffc0080
	s_addc_u32 s65, s63, -1
	s_add_i32 s93, 0, 0x10000
	s_cmp_eq_u32 s92, 12
	s_cselect_b32 s67, s17, s65
	s_cselect_b32 s66, s53, s64
	s_cselect_b32 s65, s15, s91
	s_cselect_b32 s64, s61, s90
	s_add_i32 s56, 0, 0x14000
	s_branch .Lrot_head_o
.Lrot_exit_o:
	s_barrier
	v_readlane_b32 s56, v243, 62
	v_readlane_b32 s57, v243, 63
	s_and_b64 vcc, exec, s[56:57]
	s_cbranch_vccz .LBB0_1190
	s_barrier
